# v11 plus: the two scan workgroups of one (b,head) are blocks b and b+8 (same XCD under round-robin placement) so their shared W/QG chunk loads can hit L2
# baseline (speedup 1.0000x reference)
.LBB0_1376:
	s_and_b64 vcc, exec, s[2:3]
	s_cbranch_vccz .LBB0_1387
	v_readlane_b32 s6, v253, 0
	s_waitcnt vmcnt(0) lgkmcnt(0)
	v_mov_b32_e32 v2, v160
	s_movk_i32 s2, 0x101
	s_and_b32 s4, s6, 7
	s_mul_i32 s4, s4, 0x102
	v_cmp_lt_i32_e32 vcc, s2, v2
	s_and_saveexec_b64 s[2:3], vcc
	s_xor_b64 s[2:3], exec, s[2:3]
	s_or_saveexec_b64 s[2:3], s[2:3]
	v_mov_b32_e32 v50, s4
	s_xor_b64 exec, exec, s[2:3]
	s_cbranch_execz .LBB0_1379
	v_add_u32_e32 v4, s4, v2
	v_ashrrev_i32_e32 v5, 31, v4
	v_lshl_add_u64 v[4:5], v[4:5], 2, v[0:1]
	v_add_co_u32_e32 v4, vcc, 0x50a0000, v4
	v_lshl_add_u32 v3, v2, 2, v195
	s_nop 0
	v_addc_co_u32_e32 v5, vcc, 0, v5, vcc
	global_load_dword v4, v[4:5], off
	v_add_u32_e32 v3, 0x15800, v3
	v_mov_b32_e32 v50, s4
	s_waitcnt vmcnt(0)
	ds_write_b32 v3, v4
.LBB0_1379:
	s_or_b64 exec, exec, s[2:3]
	v_readfirstlane_b32 s10, v0
	v_readfirstlane_b32 s11, v1
	v_readfirstlane_b32 s8, v2
	s_nop 3
	s_lshr_b32 s8, s8, 6
	s_lshr_b32 s5, s6, 3
	s_and_b32 s7, s6, 7
	s_mul_i32 s9, s4, 0x2000
	s_add_u32 s12, s10, s9
	s_addc_u32 s13, s11, 0
	s_add_u32 s14, s12, 0x1020000
	s_addc_u32 s15, s13, 0
	s_add_u32 s16, s12, 0x2040000
	s_addc_u32 s17, s13, 0
	s_add_u32 s18, s12, 0x3060000
	s_addc_u32 s19, s13, 0
	s_cmp_lt_u32 s8, 4
	s_cbranch_scc0 .Ldn_loader
	s_cmp_lt_u32 s8, 2
	s_cbranch_scc0 .Ldn_idle
	s_lshl_b32 s3, s5, 1
	s_add_u32 s3, s3, s8
	v_and_b32_e32 v3, 63, v2
	v_and_b32_e32 v4, 15, v2
	v_bfe_u32 v5, v2, 4, 2
	v_mul_u32_u24_e32 v6, 0x90, v4
	v_lshl_add_u32 v6, v5, 3, v6
	v_add_u32_e32 v42, v195, v6
	v_lshlrev_b32_e32 v6, 5, v3
	s_lshl_b32 s9, s3, 11
	v_add3_u32 v43, v195, v6, s9
	v_add_u32_e32 v44, 0x15800, v195
	v_lshlrev_b32_e32 v6, 12, v5
	v_and_b32_e32 v7, 3, v4
	v_lshl_add_u32 v6, v7, 10, v6
	v_lshrrev_b32_e32 v7, 2, v4
	v_lshl_add_u32 v45, v7, 4, v6
	v_and_b32_e32 v6, 1, v2
	v_cmp_eq_u32_e64 s[24:25], 1, v6
	v_and_b32_e32 v6, 2, v2
	v_cmp_eq_u32_e64 s[28:29], 2, v6
	s_nop 3
	s_not_b64 s[26:27], s[24:25]
	s_not_b64 s[30:31], s[28:29]
	v_add_u32_e32 v46, 0x4000, v45
	v_add_u32_e32 v47, 0x8000, v45
	v_add_u32_e32 v48, 0xc000, v45
	s_lshr_b32 s22, s7, 2
	s_mul_i32 s22, s22, 0x1020000
	s_and_b32 s23, s7, 3
	s_lshl_b32 s23, s23, 8
	s_add_u32 s22, s22, s23
	s_lshl_b32 s23, s3, 6
	s_add_u32 s22, s22, s23
	s_add_u32 s22, s22, 0x50a2100
	s_add_u32 s20, s10, s22
	s_addc_u32 s21, s11, 0
	v_mov_b32_e32 v50, 0
	v_mov_b32_e32 v51, 0
	v_mov_b32_e32 v52, 0
	v_mov_b32_e32 v53, 0
	v_mov_b32_e32 v54, 0
	v_mov_b32_e32 v55, 0
	v_mov_b32_e32 v56, 0
	v_mov_b32_e32 v57, 0
	v_mov_b32_e32 v58, 0
	v_mov_b32_e32 v59, 0
	v_mov_b32_e32 v60, 0
	v_mov_b32_e32 v61, 0
	v_mov_b32_e32 v62, 0
	v_mov_b32_e32 v63, 0
	v_mov_b32_e32 v64, 0
	v_mov_b32_e32 v65, 0
	v_mov_b32_e32 v66, 0
	v_mov_b32_e32 v67, 0
	v_mov_b32_e32 v68, 0
	v_mov_b32_e32 v69, 0
	v_mov_b32_e32 v70, 0
	v_mov_b32_e32 v71, 0
	v_mov_b32_e32 v72, 0
	v_mov_b32_e32 v73, 0
	s_mov_b32 s22, 0
	s_waitcnt lgkmcnt(0)
	s_barrier
